# rowpass row loop software-pipelined: next row pair's loads issued at the top of the current iteration into a second register set
# speedup vs baseline: 1.0116x; 1.0030x over previous
; DEV void unpack8(const u32x4 v, float (&f)[8]) { f[0] = bflo(v.x); f[1] = bfhi(v.x); f[2] = bflo(v.y); f[3] = bfhi(v.y); f[4] = bflo(v.z); f[5] = bfhi(v.z); f[6] = bflo(v.w); f[7] = bfhi(v.w); }
; DEV void phase_rowpass(const bf16_t* P, const float* conv_a, const float* lng, const float* lnb, bf16_t* OA, bf16_t* VN, const float* GLA, const float* GFA) {
;     ...
;     f32x4 g0[2], g1[2], b0[2], b1[2];
; #pragma unroll
;     for (int hlf = 0; hlf < 2; ++hlf) { const int c = hlf * 512 + lane * 8; g0[hlf] = *(const f32x4*)(lng + c); g1[hlf] = *(const f32x4*)(lng + c + 4); b0[hlf] = *(const f32x4*)(lnb + c); b1[hlf] = *(const f32x4*)(lnb + c + 4); }
;     for (int rp = blockIdx.x * 8 + wave; rp < T_ / 2; rp += gridDim.x * 8) {
;         const int row = rp * 2;
;         const bf16_t* pr = P + (size_t)row * NP;
;         u32x4 vr[2][2];
; #pragma unroll
;         for (int r = 0; r < 2; ++r)
; #pragma unroll
;             for (int hlf = 0; hlf < 2; ++hlf) vr[r][hlf] = *(const u32x4*)(pr + (size_t)r * NP + COL_V + hlf * 512 + lane * 8);
; #pragma unroll
;         for (int r = 0; r < 2; ++r) {
;             float v[2][8]; float sm = 0.f;
; #pragma unroll
;             for (int hlf = 0; hlf < 2; ++hlf) { unpack8(vr[r][hlf], v[hlf]);
; #pragma unroll
;                 for (int j = 0; j < 8; ++j) sm += v[hlf][j]; }
.LBB0_299:
	s_or_b64 exec, exec, s[4:5]
	v_ashrrev_i32_e32 v36, 6, v18
	v_add_u32_e32 v46, s89, v36
	s_movk_i32 s4, 0x2000
	v_cmp_gt_i32_e32 vcc, s4, v46
	s_and_saveexec_b64 s[40:41], vcc
	s_cbranch_execz .LBB0_302
	s_lshl_b32 s4, s14, 10
	s_ashr_i32 s5, s4, 31
	s_lshl_b64 s[4:5], s[4:5], 2
	s_waitcnt lgkmcnt(0)
	s_add_u32 s6, s44, s4
	v_lshlrev_b32_e32 v0, 3, v18
	s_addc_u32 s7, s45, s5
	v_and_b32_e32 v38, 0x1f8, v0
	s_add_u32 s4, s46, s4
	v_lshlrev_b32_e32 v0, 2, v38
	s_addc_u32 s5, s47, s5
	global_load_dwordx4 v[2:5], v0, s[6:7]
	global_load_dwordx4 v[6:9], v0, s[6:7] offset:16
	global_load_dwordx4 v[10:13], v0, s[6:7] offset:2048
	global_load_dwordx4 v[14:17], v0, s[6:7] offset:2064
	global_load_dwordx4 v[18:21], v0, s[4:5] offset:2048
	global_load_dwordx4 v[22:25], v0, s[4:5] offset:2064
	global_load_dwordx4 v[26:29], v0, s[4:5]
	global_load_dwordx4 v[30:33], v0, s[4:5] offset:16
	v_and_b32_e32 v0, 64, v213
	v_add_u32_e32 v0, 64, v0
	v_xor_b32_e32 v34, 32, v213
	v_cmp_lt_i32_e32 vcc, v34, v0
	v_readlane_b32 s5, v254, 32
	s_lshl_b32 s4, s71, 3
	v_cndmask_b32_e32 v34, v213, v34, vcc
	v_lshlrev_b32_e32 v47, 2, v34
	v_xor_b32_e32 v34, 16, v213
	v_cmp_lt_i32_e32 vcc, v34, v0
	v_lshl_add_u32 v36, v36, 1, s5
	s_lshl_b32 s5, s71, 4
	v_cndmask_b32_e32 v34, v213, v34, vcc
	v_lshlrev_b32_e32 v48, 2, v34
	v_xor_b32_e32 v34, 8, v213
	v_cmp_lt_i32_e32 vcc, v34, v0
	s_mov_b64 s[42:43], 0
	s_nop 0
	v_cndmask_b32_e32 v34, v213, v34, vcc
	v_lshlrev_b32_e32 v49, 2, v34
	v_xor_b32_e32 v34, 4, v213
	v_cmp_lt_i32_e32 vcc, v34, v0
	s_nop 1
	v_cndmask_b32_e32 v34, v213, v34, vcc
	v_lshlrev_b32_e32 v50, 2, v34
	v_xor_b32_e32 v34, 2, v213
	v_cmp_lt_i32_e32 vcc, v34, v0
	s_nop 1
	v_cndmask_b32_e32 v34, v213, v34, vcc
	v_lshlrev_b32_e32 v51, 2, v34
	v_xor_b32_e32 v34, 1, v213
	v_cmp_lt_i32_e32 vcc, v34, v0
	s_nop 1
	v_cndmask_b32_e32 v0, v213, v34, vcc
	v_lshlrev_b32_e32 v52, 2, v0
	v_lshlrev_b32_e32 v0, 1, v38
	v_lshl_add_u64 v[34:35], s[34:35], 0, v[0:1]
	v_lshlrev_b32_e32 v0, 1, v38
	v_mov_b64_e32 v[104:105], s[76:77]
	v_mad_i64_i32 v[104:105], s[6:7], v36, s59, v[104:105]
	v_lshl_add_u64 v[106:107], v[104:105], 0, v[0:1]
	s_mov_b64 s[6:7], 0x3000
	v_lshl_add_u64 v[104:105], v[106:107], 0, s[6:7]
	global_load_dwordx4 v[88:91], v[104:105], off offset:1024
	s_mov_b64 s[6:7], 0x3400
	v_lshl_add_u64 v[108:109], v[106:107], 0, s[6:7]
	global_load_dwordx4 v[92:95], v[108:109], off offset:1024
	s_mov_b64 s[6:7], 0x8000
	v_lshl_add_u64 v[110:111], v[106:107], 0, s[6:7]
	global_load_dwordx4 v[96:99], v[110:111], off offset:2560
	s_mov_b64 s[6:7], 0x8a00
	v_lshl_add_u64 v[104:105], v[106:107], 0, s[6:7]
	global_load_dwordx4 v[100:103], v[104:105], off offset:1024
	s_waitcnt vmcnt(0)
.LBB0_301:
	v_mov_b64_e32 v[38:39], v[88:89]
	v_mov_b64_e32 v[40:41], v[90:91]
	v_mov_b64_e32 v[42:43], v[92:93]
	v_mov_b64_e32 v[44:45], v[94:95]
	v_mov_b64_e32 v[78:79], v[96:97]
	v_mov_b64_e32 v[80:81], v[98:99]
	v_mov_b64_e32 v[82:83], v[100:101]
	v_mov_b64_e32 v[84:85], v[102:103]
	v_add_u32_e32 v46, s4, v46
	v_add_u32_e32 v113, s5, v36
	s_movk_i32 s6, 0x2000
	v_cmp_gt_i32_e32 vcc, s6, v46
	s_nop 1
	v_cndmask_b32_e32 v112, v36, v113, vcc
	v_mov_b64_e32 v[104:105], s[76:77]
	v_mad_i64_i32 v[104:105], s[6:7], v112, s59, v[104:105]
	v_lshl_add_u64 v[106:107], v[104:105], 0, v[0:1]
	s_mov_b64 s[6:7], 0x3000
	v_lshl_add_u64 v[104:105], v[106:107], 0, s[6:7]
	global_load_dwordx4 v[88:91], v[104:105], off offset:1024
	s_mov_b64 s[6:7], 0x3400
	v_lshl_add_u64 v[108:109], v[106:107], 0, s[6:7]
	global_load_dwordx4 v[92:95], v[108:109], off offset:1024
	s_mov_b64 s[6:7], 0x8000
	v_lshl_add_u64 v[110:111], v[106:107], 0, s[6:7]
	global_load_dwordx4 v[96:99], v[110:111], off offset:2560
	s_mov_b64 s[6:7], 0x8a00
	v_lshl_add_u64 v[104:105], v[106:107], 0, s[6:7]
	global_load_dwordx4 v[100:103], v[104:105], off offset:1024
	s_movk_i32 s6, 0x1fff
	v_lshlrev_b32_e32 v72, 16, v38
	v_and_b32_e32 v71, 0xffff0000, v38
	v_add_f32_e32 v37, 0, v72
	v_lshlrev_b32_e32 v70, 16, v39
	v_add_f32_e32 v37, v37, v71
	v_and_b32_e32 v69, 0xffff0000, v39
	v_add_f32_e32 v37, v37, v70
	v_lshlrev_b32_e32 v76, 16, v40
	v_add_f32_e32 v37, v37, v69
	v_and_b32_e32 v75, 0xffff0000, v40
	v_add_f32_e32 v37, v37, v76
	v_lshlrev_b32_e32 v74, 16, v41
	v_add_f32_e32 v37, v37, v75
	v_and_b32_e32 v73, 0xffff0000, v41
	v_add_f32_e32 v37, v37, v74
	v_lshlrev_b32_e32 v68, 16, v42
	v_add_f32_e32 v37, v37, v73
	v_and_b32_e32 v67, 0xffff0000, v42
	v_add_f32_e32 v37, v37, v68
	v_lshlrev_b32_e32 v66, 16, v43
	v_add_f32_e32 v37, v37, v67
	v_and_b32_e32 v65, 0xffff0000, v43
	v_add_f32_e32 v37, v37, v66
	v_lshlrev_b32_e32 v87, 16, v44
	v_add_f32_e32 v37, v37, v65
	v_and_b32_e32 v86, 0xffff0000, v44
	v_add_f32_e32 v37, v37, v87
	v_lshlrev_b32_e32 v43, 16, v45
	v_add_f32_e32 v37, v37, v86
	v_and_b32_e32 v42, 0xffff0000, v45
	v_add_f32_e32 v37, v37, v43
	v_add_f32_e32 v37, v37, v42
	ds_bpermute_b32 v45, v47, v37
	v_lshlrev_b32_e32 v63, 16, v78
	v_and_b32_e32 v61, 0xffff0000, v78
	v_add_f32_e32 v44, 0, v63
	v_lshlrev_b32_e32 v59, 16, v79
	v_add_f32_e32 v44, v44, v61
	v_and_b32_e32 v57, 0xffff0000, v79
	v_add_f32_e32 v44, v44, v59
	v_lshlrev_b32_e32 v64, 16, v80
	v_add_f32_e32 v44, v44, v57
	s_waitcnt lgkmcnt(0)
	v_add_f32_e32 v37, v37, v45
	v_and_b32_e32 v62, 0xffff0000, v80
	v_add_f32_e32 v44, v44, v64
	ds_bpermute_b32 v45, v48, v37
	v_lshlrev_b32_e32 v60, 16, v81
	v_add_f32_e32 v44, v44, v62
	v_and_b32_e32 v58, 0xffff0000, v81
	v_add_f32_e32 v44, v44, v60
	v_lshlrev_b32_e32 v56, 16, v82
	v_add_f32_e32 v44, v44, v58
	v_and_b32_e32 v55, 0xffff0000, v82
	v_add_f32_e32 v44, v44, v56
	v_lshlrev_b32_e32 v54, 16, v83
	v_add_f32_e32 v44, v44, v55
	s_waitcnt lgkmcnt(0)
; DEV void unpack8(const u32x4 v, float (&f)[8]) { f[0] = bflo(v.x); f[1] = bfhi(v.x); f[2] = bflo(v.y); f[3] = bfhi(v.y); f[4] = bflo(v.z); f[5] = bfhi(v.z); f[6] = bflo(v.w); f[7] = bfhi(v.w); }
; DEV void phase_rowpass(const bf16_t* P, const float* conv_a, const float* lng, const float* lnb, bf16_t* OA, bf16_t* VN, const float* GLA, const float* GFA) {
;     ...
;         for (int r = 0; r < 2; ++r) {
;             float v[2][8]; float sm = 0.f;
; #pragma unroll
;             for (int hlf = 0; hlf < 2; ++hlf) { unpack8(vr[r][hlf], v[hlf]);
; #pragma unroll
;                 for (int j = 0; j < 8; ++j) sm += v[hlf][j]; }
;             const float mu = wave_sum(sm) * (1.f / 1024.f);
;             float q = 0.f;
; #pragma unroll
;             for (int hlf = 0; hlf < 2; ++hlf)
; #pragma unroll
;                 for (int j = 0; j < 8; ++j) { const float d = v[hlf][j] - mu; q += d * d; }
;             const float rstd = rsqrtf(wave_sum(q) * (1.f / 1024.f) + EPS_);
	v_add_f32_e32 v37, v37, v45
	v_and_b32_e32 v53, 0xffff0000, v83
	v_add_f32_e32 v44, v44, v54
	ds_bpermute_b32 v45, v49, v37
	v_lshlrev_b32_e32 v41, 16, v84
	v_add_f32_e32 v44, v44, v53
	v_and_b32_e32 v40, 0xffff0000, v84
	v_add_f32_e32 v44, v44, v41
	v_lshlrev_b32_e32 v39, 16, v85
	v_add_f32_e32 v44, v44, v40
	v_and_b32_e32 v38, 0xffff0000, v85
	v_add_f32_e32 v44, v44, v39
	v_add_f32_e32 v44, v44, v38
	s_waitcnt lgkmcnt(0)
	v_add_f32_e32 v37, v37, v45
	ds_bpermute_b32 v77, v47, v44
	ds_bpermute_b32 v45, v50, v37
	s_waitcnt lgkmcnt(1)
	v_add_f32_e32 v44, v44, v77
	s_waitcnt lgkmcnt(0)
	v_add_f32_e32 v37, v37, v45
	ds_bpermute_b32 v77, v48, v44
	ds_bpermute_b32 v45, v51, v37
	s_waitcnt lgkmcnt(1)
	v_add_f32_e32 v44, v44, v77
	s_waitcnt lgkmcnt(0)
	v_add_f32_e32 v37, v37, v45
	ds_bpermute_b32 v77, v49, v44
	ds_bpermute_b32 v45, v52, v37
	s_waitcnt lgkmcnt(1)
	v_add_f32_e32 v44, v44, v77
	s_waitcnt lgkmcnt(0)
	v_add_f32_e32 v37, v37, v45
	ds_bpermute_b32 v77, v50, v44
	v_fmac_f32_e32 v71, 0xba800000, v37
	v_mul_f32_e32 v80, 0x3a800000, v37
	v_fmac_f32_e32 v72, 0xba800000, v37
	v_fmac_f32_e32 v70, 0xba800000, v37
	v_fmac_f32_e32 v69, 0xba800000, v37
	v_fmac_f32_e32 v76, 0xba800000, v37
	v_fmac_f32_e32 v75, 0xba800000, v37
	v_fmac_f32_e32 v74, 0xba800000, v37
	v_fmac_f32_e32 v73, 0xba800000, v37
	v_fmac_f32_e32 v68, 0xba800000, v37
	v_fmac_f32_e32 v67, 0xba800000, v37
	v_fmac_f32_e32 v66, 0xba800000, v37
	v_fmac_f32_e32 v65, 0xba800000, v37
	v_mul_f32_e32 v37, v71, v71
	v_fmac_f32_e32 v37, v72, v72
	v_fmac_f32_e32 v37, v70, v70
	v_fmac_f32_e32 v37, v69, v69
	s_waitcnt lgkmcnt(0)
	v_add_f32_e32 v44, v44, v77
	v_fmac_f32_e32 v37, v76, v76
	ds_bpermute_b32 v77, v51, v44
	v_fmac_f32_e32 v37, v75, v75
	v_fmac_f32_e32 v37, v74, v74
	v_fmac_f32_e32 v37, v73, v73
	v_fmac_f32_e32 v37, v68, v68
	v_fmac_f32_e32 v37, v67, v67
	s_waitcnt lgkmcnt(0)
	v_add_f32_e32 v77, v44, v77
	v_pk_add_f32 v[44:45], v[86:87], v[80:81] op_sel_hi:[1,0] neg_lo:[0,1] neg_hi:[0,1]
	v_fmac_f32_e32 v37, v66, v66
	v_pk_add_f32 v[42:43], v[42:43], v[80:81] op_sel_hi:[1,0] neg_lo:[0,1] neg_hi:[0,1]
	v_pk_mul_f32 v[80:81], v[44:45], v[44:45]
	v_fmac_f32_e32 v37, v65, v65
	v_add_f32_e32 v37, v81, v37
	v_pk_mul_f32 v[82:83], v[42:43], v[42:43]
	v_add_f32_e32 v37, v80, v37
	v_add_f32_e32 v37, v83, v37
	v_add_f32_e32 v79, v82, v37
	ds_bpermute_b32 v78, v52, v77
	ds_bpermute_b32 v80, v47, v79
	v_ashrrev_i32_e32 v37, 31, v36
	v_lshlrev_b64 v[82:83], 11, v[36:37]
	s_waitcnt lgkmcnt(1)
	v_add_f32_e32 v37, v77, v78
	s_waitcnt lgkmcnt(0)
	v_add_f32_e32 v77, v79, v80
	ds_bpermute_b32 v79, v48, v77
	v_mul_f32_e32 v78, 0x3a800000, v37
	v_fmac_f32_e32 v63, 0xba800000, v37
	v_fmac_f32_e32 v61, 0xba800000, v37
	v_fmac_f32_e32 v59, 0xba800000, v37
	s_waitcnt lgkmcnt(0)
	v_add_f32_e32 v77, v77, v79
	ds_bpermute_b32 v79, v49, v77
	v_fmac_f32_e32 v57, 0xba800000, v37
	v_fmac_f32_e32 v64, 0xba800000, v37
	v_fmac_f32_e32 v62, 0xba800000, v37
	v_fmac_f32_e32 v60, 0xba800000, v37
	s_waitcnt lgkmcnt(0)
	v_add_f32_e32 v77, v77, v79
	ds_bpermute_b32 v79, v50, v77
	v_fmac_f32_e32 v58, 0xba800000, v37
	v_fmac_f32_e32 v56, 0xba800000, v37
	v_fmac_f32_e32 v55, 0xba800000, v37
	v_fmac_f32_e32 v54, 0xba800000, v37
	v_fmac_f32_e32 v53, 0xba800000, v37
	s_waitcnt lgkmcnt(0)
	v_add_f32_e32 v37, v77, v79
	ds_bpermute_b32 v77, v51, v37
	v_mul_f32_e32 v79, v61, v61
	v_fmac_f32_e32 v79, v63, v63
	v_fmac_f32_e32 v79, v59, v59
	v_fmac_f32_e32 v79, v57, v57
	s_waitcnt lgkmcnt(0)
	v_add_f32_e32 v37, v37, v77
	ds_bpermute_b32 v77, v52, v37
	v_fmac_f32_e32 v79, v64, v64
	v_fmac_f32_e32 v79, v62, v62
	v_fmac_f32_e32 v79, v60, v60
	v_fmac_f32_e32 v79, v58, v58
	s_waitcnt lgkmcnt(0)
; DEV u32x4 pack8(const float (&f)[8]) { u32x4 w; w.x = cvt_pk_bf16(f[0], f[1]); w.y = cvt_pk_bf16(f[2], f[3]); w.z = cvt_pk_bf16(f[4], f[5]); w.w = cvt_pk_bf16(f[6], f[7]); return w; }
; DEV void phase_rowpass(const bf16_t* P, const float* conv_a, const float* lng, const float* lnb, bf16_t* OA, bf16_t* VN, const float* GLA, const float* GFA) {
;     ...
;             const float rstd = rsqrtf(wave_sum(q) * (1.f / 1024.f) + EPS_);
; #pragma unroll
;             for (int hlf = 0; hlf < 2; ++hlf) { const int c = hlf * 512 + lane * 8; float o[8];
; #pragma unroll
;                 for (int j = 0; j < 4; ++j) { o[j] = (v[hlf][j] - mu) * rstd * g0[hlf][j] + b0[hlf][j]; o[4 + j] = (v[hlf][4 + j] - mu) * rstd * g1[hlf][j] + b1[hlf][j]; }
;                 *(u32x4*)(VN + (size_t)(row + r) * 1024 + c) = pack8(o); }
;         }
;     }
	v_add_f32_e32 v37, v37, v77
	v_fmamk_f32 v37, v37, 0x3a800000, v211
	v_mul_f32_e32 v77, 0x4b800000, v37
	v_cmp_gt_f32_e32 vcc, s33, v37
	v_fmac_f32_e32 v79, v56, v56
	v_fmac_f32_e32 v79, v55, v55
	v_cndmask_b32_e32 v37, v37, v77, vcc
	v_rsq_f32_e32 v37, v37
	v_fmac_f32_e32 v79, v54, v54
	v_fmac_f32_e32 v79, v53, v53
	v_pk_add_f32 v[40:41], v[40:41], v[78:79] op_sel_hi:[1,0] neg_lo:[0,1] neg_hi:[0,1]
	v_mul_f32_e32 v77, 0x45800000, v37
	v_cndmask_b32_e32 v37, v37, v77, vcc
	v_mul_f32_e32 v71, v71, v37
	v_mul_f32_e32 v70, v70, v37
	v_fma_f32 v77, v3, v71, v27
	v_fma_f32 v80, v4, v70, v28
	v_pk_mul_f32 v[70:71], v[40:41], v[40:41]
	v_mul_f32_e32 v69, v69, v37
	v_add_f32_e32 v71, v71, v79
	v_add_f32_e32 v79, v70, v71
	v_pk_add_f32 v[38:39], v[38:39], v[78:79] op_sel_hi:[1,0] neg_lo:[0,1] neg_hi:[0,1]
	v_mul_f32_e32 v72, v72, v37
	v_pk_mul_f32 v[70:71], v[38:39], v[38:39]
	v_mul_f32_e32 v76, v76, v37
	v_add_f32_e32 v71, v71, v79
	v_add_f32_e32 v78, v70, v71
	ds_bpermute_b32 v79, v47, v78
	v_fma_f32 v69, v5, v69, v29
	v_mul_f32_e32 v75, v75, v37
	v_fma_f32 v72, v2, v72, v26
	v_fma_f32 v76, v6, v76, v30
	v_cvt_pk_bf16_f32 v70, v72, v77
	v_cvt_pk_bf16_f32 v71, v80, v69
	s_waitcnt lgkmcnt(0)
	v_add_f32_e32 v69, v78, v79
	v_fma_f32 v75, v7, v75, v31
	v_cvt_pk_bf16_f32 v72, v76, v75
	ds_bpermute_b32 v76, v48, v69
	v_mul_f32_e32 v74, v74, v37
	v_mul_f32_e32 v73, v73, v37
	v_fma_f32 v74, v8, v74, v32
	v_fma_f32 v73, v9, v73, v33
	v_cvt_pk_bf16_f32 v73, v74, v73
	v_lshl_add_u64 v[74:75], v[34:35], 0, v[82:83]
	s_waitcnt lgkmcnt(0)
	v_add_f32_e32 v69, v69, v76
	global_store_dwordx4 v[74:75], v[70:73], off
	ds_bpermute_b32 v70, v49, v69
	v_mul_f32_e32 v43, v43, v37
	v_fma_f32 v71, v16, v43, v24
	v_mul_f32_e32 v43, v65, v37
	v_mul_f32_e32 v66, v66, v37
	s_waitcnt lgkmcnt(0)
	v_add_f32_e32 v69, v69, v70
	ds_bpermute_b32 v70, v50, v69
	v_mul_f32_e32 v68, v68, v37
	v_mul_f32_e32 v67, v67, v37
	v_fma_f32 v66, v12, v66, v20
	v_fma_f32 v43, v13, v43, v21
	s_waitcnt lgkmcnt(0)
	v_add_f32_e32 v69, v69, v70
	ds_bpermute_b32 v70, v51, v69
	v_fma_f32 v68, v10, v68, v18
	v_mul_f32_e32 v45, v45, v37
	v_fma_f32 v67, v11, v67, v19
	v_mul_f32_e32 v44, v44, v37
	s_waitcnt lgkmcnt(0)
	v_add_f32_e32 v65, v69, v70
	ds_bpermute_b32 v69, v52, v65
	v_mul_f32_e32 v37, v42, v37
	v_cvt_pk_bf16_f32 v42, v68, v67
	v_cvt_pk_bf16_f32 v43, v66, v43
	v_fma_f32 v45, v14, v45, v22
	s_waitcnt lgkmcnt(0)
	v_add_f32_e32 v65, v65, v69
	v_fmamk_f32 v65, v65, 0x3a800000, v211
	v_mul_f32_e32 v66, 0x4b800000, v65
	v_cmp_gt_f32_e32 vcc, s33, v65
	v_fma_f32 v44, v15, v44, v23
	v_fma_f32 v37, v17, v37, v25
	v_cndmask_b32_e32 v65, v65, v66, vcc
	v_rsq_f32_e32 v65, v65
	v_cvt_pk_bf16_f32 v44, v45, v44
	v_cvt_pk_bf16_f32 v45, v71, v37
	global_store_dwordx4 v[74:75], v[42:45], off offset:1024
	v_mul_f32_e32 v37, 0x45800000, v65
	v_cndmask_b32_e32 v37, v65, v37, vcc
	v_add_u32_e32 v42, 1, v36
	v_ashrrev_i32_e32 v43, 31, v42
	v_lshlrev_b64 v[66:67], 11, v[42:43]
	v_mul_f32_e32 v43, v64, v37
	v_mul_f32_e32 v42, v63, v37
	v_fma_f32 v44, v6, v43, v30
	v_mul_f32_e32 v43, v61, v37
	v_mul_f32_e32 v45, v62, v37
	v_mul_f32_e32 v59, v59, v37
	v_mul_f32_e32 v58, v58, v37
	v_fma_f32 v42, v2, v42, v26
	v_fma_f32 v43, v3, v43, v27
	v_fma_f32 v45, v7, v45, v31
	v_fma_f32 v59, v4, v59, v28
	v_mul_f32_e32 v60, v60, v37
	v_mul_f32_e32 v57, v57, v37
	v_fma_f32 v58, v9, v58, v33
	v_fma_f32 v60, v8, v60, v32
	v_fma_f32 v57, v5, v57, v29
	v_cvt_pk_bf16_f32 v42, v42, v43
	v_cvt_pk_bf16_f32 v43, v59, v57
	v_cvt_pk_bf16_f32 v44, v44, v45
	v_cvt_pk_bf16_f32 v45, v60, v58
	v_lshl_add_u64 v[58:59], v[34:35], 0, v[66:67]
	v_mul_f32_e32 v39, v39, v37
	global_store_dwordx4 v[58:59], v[42:45], off
	v_mul_f32_e32 v41, v41, v37
	v_mul_f32_e32 v40, v40, v37
	v_fma_f32 v45, v16, v39, v24
	v_mul_f32_e32 v39, v53, v37
	v_cmp_lt_i32_e32 vcc, s6, v46
	v_mul_f32_e32 v42, v56, v37
	v_fma_f32 v41, v14, v41, v22
	v_mul_f32_e32 v43, v55, v37
	v_fma_f32 v40, v15, v40, v23
	v_mul_f32_e32 v44, v54, v37
	v_fma_f32 v39, v13, v39, v21
	v_mul_f32_e32 v37, v38, v37
	s_or_b64 s[42:43], vcc, s[42:43]
	v_add_u32_e32 v36, s5, v36
	v_fma_f32 v42, v10, v42, v18
	v_fma_f32 v43, v11, v43, v19
	v_fma_f32 v44, v12, v44, v20
	v_fma_f32 v37, v17, v37, v25
	v_cvt_pk_bf16_f32 v38, v42, v43
	v_cvt_pk_bf16_f32 v39, v44, v39
	v_cvt_pk_bf16_f32 v40, v41, v40
	v_cvt_pk_bf16_f32 v41, v45, v37
	global_store_dwordx4 v[58:59], v[38:41], off offset:1024
	s_waitcnt vmcnt(4)
	s_andn2_b64 exec, exec, s[42:43]
	s_cbranch_execnz .LBB0_301
